# v069 + PV group leads with its MFMA right after the barrier; the next step's K fragment reads are interleaved behind the first four PV MFMAs
# speedup vs baseline: 1.0071x; 1.0007x over previous
.Lattn_fx_skipw1:
	v_exp_f32_e32 v78, v78
	v_exp_f32_e32 v79, v79
	v_add_f32_e32 v246, v76, v246
	v_add_f32_e32 v246, v77, v246
	v_cvt_pk_bf16_f32 v71, v76, v77
	v_mfma_f32_32x32x16_bf16 v[98:113], v[186:189], v[138:141], v[98:113]
	v_exp_f32_e32 v80, v80
	v_exp_f32_e32 v81, v81
	v_add_f32_e32 v246, v78, v246
	v_add_f32_e32 v246, v79, v246
	v_cvt_pk_bf16_f32 v72, v78, v79
	v_mfma_f32_32x32x16_bf16 v[114:129], v[174:177], v[142:145], v[114:129]
	v_exp_f32_e32 v34, v34
	v_exp_f32_e32 v35, v35
	v_add_f32_e32 v246, v80, v246
	v_add_f32_e32 v246, v81, v246
	v_cvt_pk_bf16_f32 v73, v80, v81
	v_mfma_f32_32x32x16_bf16 v[98:113], v[82:85], v[142:145], v[98:113]
	v_exp_f32_e32 v36, v36
	v_exp_f32_e32 v37, v37
	v_add_f32_e32 v247, v34, v35
	v_cvt_pk_bf16_f32 v74, v34, v35
	s_waitcnt lgkmcnt(0)
	s_barrier
	v_mfma_f32_32x32x16_bf16 v[18:33], v[86:89], v[66:69], v[18:33]
	ds_read_b128 v[162:165], v193 offset:18432
	ds_read_b128 v[178:181], v193 offset:23040
	v_exp_f32_e32 v38, v38
	v_exp_f32_e32 v39, v39
	v_add_f32_e32 v247, v36, v247
	v_add_f32_e32 v247, v37, v247
	v_cvt_pk_bf16_f32 v75, v36, v37
	v_mfma_f32_32x32x16_bf16 v[2:17], v[216:219], v[66:69], v[2:17]
	ds_read_b128 v[166:169], v193 offset:18464
	ds_read_b128 v[182:185], v193 offset:23072
	v_exp_f32_e32 v40, v40
	v_exp_f32_e32 v41, v41
	v_add_f32_e32 v247, v38, v247
	v_add_f32_e32 v247, v39, v247
	v_cvt_pk_bf16_f32 v76, v38, v39
	v_mfma_f32_32x32x16_bf16 v[18:33], v[90:93], v[70:73], v[18:33]
	ds_read_b128 v[170:173], v193 offset:18496
	ds_read_b128 v[186:189], v193 offset:23104
	v_exp_f32_e32 v42, v42
	v_exp_f32_e32 v43, v43
	v_add_f32_e32 v247, v40, v247
	v_add_f32_e32 v247, v41, v247
	v_cvt_pk_bf16_f32 v77, v40, v41
	v_mfma_f32_32x32x16_bf16 v[2:17], v[220:223], v[70:73], v[2:17]
	ds_read_b128 v[174:177], v193 offset:18528
	ds_read_b128 v[82:85], v193 offset:23136
	v_exp_f32_e32 v44, v44
	v_exp_f32_e32 v45, v45
	v_add_f32_e32 v247, v42, v247
	v_add_f32_e32 v247, v43, v247
	v_cvt_pk_bf16_f32 v78, v42, v43
	v_mfma_f32_32x32x16_bf16 v[18:33], v[94:97], v[74:77], v[18:33]
	v_exp_f32_e32 v46, v46
	v_exp_f32_e32 v47, v47
	v_add_f32_e32 v247, v44, v247
	v_add_f32_e32 v247, v45, v247
	v_cvt_pk_bf16_f32 v79, v44, v45
	v_mfma_f32_32x32x16_bf16 v[2:17], v[224:227], v[74:77], v[2:17]
	v_exp_f32_e32 v48, v48
	v_exp_f32_e32 v49, v49
	v_add_f32_e32 v247, v46, v247
	v_add_f32_e32 v247, v47, v247
	v_cvt_pk_bf16_f32 v80, v46, v47
	v_cvt_pk_bf16_f32 v81, v48, v49
	v_add_f32_e32 v247, v48, v247
	v_add_f32_e32 v247, v49, v247
	v_mfma_f32_32x32x16_bf16 v[18:33], v[212:215], v[78:81], v[18:33]
	v_mfma_f32_32x32x16_bf16 v[2:17], v[242:245], v[78:81], v[2:17]
	v_add_f32_e32 v210, v210, v246
	v_add_f32_e32 v210, v210, v247
	s_min_i32 s24, s10, s58
	s_mul_i32 s44, s24, 0xa0000
	s_add_u32 s44, s3, s44
	s_addc_u32 s45, s12, 0
	s_lshl_b32 s46, s24, 7
	s_add_u32 s46, s15, s46
	s_addc_u32 s47, s23, 0
	global_load_dwordx4 v[146:149], v252, s[44:45] offset:1024
	global_load_dwordx4 v[150:153], v253, s[46:47]
	v_exp_f32_e32 v114, v114
	v_exp_f32_e32 v115, v115
	v_exp_f32_e32 v116, v116
	v_exp_f32_e32 v117, v117
	v_add_f32_e32 v246, v114, v115
	v_cvt_pk_bf16_f32 v114, v114, v115
	s_waitcnt lgkmcnt(0)
	v_mfma_f32_32x32x16_bf16 v[66:81], v[162:165], v[130:133], v[50:65]
	ds_read_b128 v[86:89], v248
	ds_read_b128 v[216:219], v248 offset:4608
	v_exp_f32_e32 v118, v118
	v_exp_f32_e32 v119, v119
	v_add_f32_e32 v246, v116, v246
	v_add_f32_e32 v246, v117, v246
	v_cvt_pk_bf16_f32 v115, v116, v117
	v_mfma_f32_32x32x16_bf16 v[34:49], v[178:181], v[130:133], v[50:65]
	ds_read_b128 v[90:93], v248 offset:32
	ds_read_b128 v[220:223], v248 offset:4640
	v_exp_f32_e32 v120, v120
	v_exp_f32_e32 v121, v121
	v_add_f32_e32 v246, v118, v246
	v_add_f32_e32 v246, v119, v246
	v_cvt_pk_bf16_f32 v116, v118, v119
	v_mfma_f32_32x32x16_bf16 v[66:81], v[166:169], v[134:137], v[66:81]
	ds_read_b128 v[94:97], v248 offset:64
	ds_read_b128 v[224:227], v248 offset:4672
	v_exp_f32_e32 v122, v122
	v_exp_f32_e32 v123, v123
	v_add_f32_e32 v246, v120, v246
	v_add_f32_e32 v246, v121, v246
	v_cvt_pk_bf16_f32 v117, v120, v121
	v_mfma_f32_32x32x16_bf16 v[34:49], v[182:185], v[134:137], v[34:49]
	ds_read_b128 v[212:215], v248 offset:96
	ds_read_b128 v[242:245], v248 offset:4704
	v_exp_f32_e32 v124, v124
	v_exp_f32_e32 v125, v125
	v_add_f32_e32 v246, v122, v246
	v_add_f32_e32 v246, v123, v246
	v_cvt_pk_bf16_f32 v118, v122, v123
	v_mfma_f32_32x32x16_bf16 v[66:81], v[170:173], v[138:141], v[66:81]
	s_cmp_ge_u32 s11, s16
	s_cbranch_scc1 .Lattn_fx_skipw2
	s_waitcnt vmcnt(2)
	ds_write_b128 v192, v[154:157] offset:55296
	ds_write_b128 v204, v[158:161] offset:64512
.Lattn_fx_skipw2:
	v_exp_f32_e32 v126, v126
	v_exp_f32_e32 v127, v127
	v_add_f32_e32 v246, v124, v246
	v_add_f32_e32 v246, v125, v246
	v_cvt_pk_bf16_f32 v119, v124, v125
	v_mfma_f32_32x32x16_bf16 v[34:49], v[186:189], v[138:141], v[34:49]
	v_exp_f32_e32 v128, v128
	v_exp_f32_e32 v129, v129
	v_add_f32_e32 v246, v126, v246
	v_add_f32_e32 v246, v127, v246
	v_cvt_pk_bf16_f32 v120, v126, v127
	v_mfma_f32_32x32x16_bf16 v[66:81], v[174:177], v[142:145], v[66:81]
	v_exp_f32_e32 v98, v98
	v_exp_f32_e32 v99, v99
	v_add_f32_e32 v246, v128, v246
	v_add_f32_e32 v246, v129, v246
	v_cvt_pk_bf16_f32 v121, v128, v129
	v_mfma_f32_32x32x16_bf16 v[34:49], v[82:85], v[142:145], v[34:49]
	v_exp_f32_e32 v100, v100
	v_exp_f32_e32 v101, v101
	v_add_f32_e32 v247, v98, v99
	v_cvt_pk_bf16_f32 v122, v98, v99
	s_waitcnt lgkmcnt(0)
	s_barrier
	v_mfma_f32_32x32x16_bf16 v[18:33], v[86:89], v[114:117], v[18:33]
	ds_read_b128 v[162:165], v193 offset:55296
	ds_read_b128 v[178:181], v193 offset:59904
	v_exp_f32_e32 v102, v102
	v_exp_f32_e32 v103, v103
	v_add_f32_e32 v247, v100, v247
	v_add_f32_e32 v247, v101, v247
	v_cvt_pk_bf16_f32 v123, v100, v101
	v_mfma_f32_32x32x16_bf16 v[2:17], v[216:219], v[114:117], v[2:17]
	ds_read_b128 v[166:169], v193 offset:55328
	ds_read_b128 v[182:185], v193 offset:59936
	v_exp_f32_e32 v104, v104
	v_exp_f32_e32 v105, v105
	v_add_f32_e32 v247, v102, v247
	v_add_f32_e32 v247, v103, v247
	v_cvt_pk_bf16_f32 v124, v102, v103
	v_mfma_f32_32x32x16_bf16 v[18:33], v[90:93], v[118:121], v[18:33]
	ds_read_b128 v[170:173], v193 offset:55360
	ds_read_b128 v[186:189], v193 offset:59968
	v_exp_f32_e32 v106, v106
	v_exp_f32_e32 v107, v107
	v_add_f32_e32 v247, v104, v247
	v_add_f32_e32 v247, v105, v247
	v_cvt_pk_bf16_f32 v125, v104, v105
	v_mfma_f32_32x32x16_bf16 v[2:17], v[220:223], v[118:121], v[2:17]
	ds_read_b128 v[174:177], v193 offset:55392
	ds_read_b128 v[82:85], v193 offset:60000
	v_exp_f32_e32 v108, v108
	v_exp_f32_e32 v109, v109
	v_add_f32_e32 v247, v106, v247
	v_add_f32_e32 v247, v107, v247
	v_cvt_pk_bf16_f32 v126, v106, v107
	v_mfma_f32_32x32x16_bf16 v[18:33], v[94:97], v[122:125], v[18:33]
	v_exp_f32_e32 v110, v110
	v_exp_f32_e32 v111, v111
	v_add_f32_e32 v247, v108, v247
	v_add_f32_e32 v247, v109, v247
	v_cvt_pk_bf16_f32 v127, v108, v109
	v_mfma_f32_32x32x16_bf16 v[2:17], v[224:227], v[122:125], v[2:17]
	v_exp_f32_e32 v112, v112
	v_exp_f32_e32 v113, v113
	v_add_f32_e32 v247, v110, v247
	v_add_f32_e32 v247, v111, v247
	v_cvt_pk_bf16_f32 v128, v110, v111
	v_cvt_pk_bf16_f32 v129, v112, v113
	v_add_f32_e32 v247, v112, v247
	v_add_f32_e32 v247, v113, v247
	v_mfma_f32_32x32x16_bf16 v[18:33], v[212:215], v[126:129], v[18:33]
	v_mfma_f32_32x32x16_bf16 v[2:17], v[242:245], v[126:129], v[2:17]
	v_add_f32_e32 v210, v210, v246
	v_add_f32_e32 v210, v210, v247
	s_add_i32 s10, s10, 2
	s_cmp_lt_u32 s11, s16
	s_cbranch_scc0 .Lattn_fx_exit0
	s_add_i32 s11, s10, -1
	s_min_i32 s1, s11, s58
	s_mul_i32 s44, s1, 0xa0000
	s_add_u32 s44, s3, s44
	s_addc_u32 s45, s12, 0
	s_lshl_b32 s46, s1, 7
	s_add_u32 s46, s15, s46
	s_addc_u32 s47, s23, 0
	s_add_i32 s24, s10, -2
	s_cmp_lt_u32 s24, s16
	s_cselect_b64 s[0:1], -1, 0
	global_load_dwordx4 v[154:157], v252, s[44:45] offset:1024
	global_load_dwordx4 v[158:161], v253, s[46:47]
	v_exp_f32_e32 v66, v66
	v_exp_f32_e32 v67, v67
	v_exp_f32_e32 v68, v68
	v_exp_f32_e32 v69, v69
	v_add_f32_e32 v246, v66, v67
	v_cvt_pk_bf16_f32 v66, v66, v67
	s_waitcnt lgkmcnt(0)
	v_mfma_f32_32x32x16_bf16 v[114:129], v[162:165], v[130:133], v[50:65]
	ds_read_b128 v[86:89], v248 offset:18432
	ds_read_b128 v[216:219], v248 offset:23040
	v_exp_f32_e32 v70, v70
	v_exp_f32_e32 v71, v71
	v_add_f32_e32 v246, v68, v246
	v_add_f32_e32 v246, v69, v246
	v_cvt_pk_bf16_f32 v67, v68, v69
	v_mfma_f32_32x32x16_bf16 v[98:113], v[178:181], v[130:133], v[50:65]
	ds_read_b128 v[90:93], v248 offset:18464
	ds_read_b128 v[220:223], v248 offset:23072
	v_exp_f32_e32 v72, v72
	v_exp_f32_e32 v73, v73
	v_add_f32_e32 v246, v70, v246
	v_add_f32_e32 v246, v71, v246
	v_cvt_pk_bf16_f32 v68, v70, v71
	v_mfma_f32_32x32x16_bf16 v[114:129], v[166:169], v[134:137], v[114:129]
	ds_read_b128 v[94:97], v248 offset:18496
	ds_read_b128 v[224:227], v248 offset:23104
	v_exp_f32_e32 v74, v74
	v_exp_f32_e32 v75, v75
	v_add_f32_e32 v246, v72, v246
	v_add_f32_e32 v246, v73, v246
	v_cvt_pk_bf16_f32 v69, v72, v73
	v_mfma_f32_32x32x16_bf16 v[98:113], v[182:185], v[134:137], v[98:113]
	ds_read_b128 v[212:215], v248 offset:18528
	ds_read_b128 v[242:245], v248 offset:23136
	v_exp_f32_e32 v76, v76
	v_exp_f32_e32 v77, v77
	v_add_f32_e32 v246, v74, v246
	v_add_f32_e32 v246, v75, v246
	v_cvt_pk_bf16_f32 v70, v74, v75
	v_mfma_f32_32x32x16_bf16 v[114:129], v[170:173], v[138:141], v[114:129]
	s_cmp_ge_u32 s24, s16
	s_cbranch_scc1 .Lattn_fx_skipw3
	s_waitcnt vmcnt(2)
	ds_write_b128 v192, v[146:149] offset:36864
	ds_write_b128 v204, v[150:153] offset:46080
.Lattn_fx_skipw3:
	v_exp_f32_e32 v78, v78
	v_exp_f32_e32 v79, v79
	v_add_f32_e32 v246, v76, v246
	v_add_f32_e32 v246, v77, v246
	v_cvt_pk_bf16_f32 v71, v76, v77
	v_mfma_f32_32x32x16_bf16 v[98:113], v[186:189], v[138:141], v[98:113]
	v_exp_f32_e32 v80, v80
	v_exp_f32_e32 v81, v81
	v_add_f32_e32 v246, v78, v246
	v_add_f32_e32 v246, v79, v246
	v_cvt_pk_bf16_f32 v72, v78, v79
	v_mfma_f32_32x32x16_bf16 v[114:129], v[174:177], v[142:145], v[114:129]
	v_exp_f32_e32 v34, v34
	v_exp_f32_e32 v35, v35
	v_add_f32_e32 v246, v80, v246
	v_add_f32_e32 v246, v81, v246
	v_cvt_pk_bf16_f32 v73, v80, v81
	v_mfma_f32_32x32x16_bf16 v[98:113], v[82:85], v[142:145], v[98:113]
	v_exp_f32_e32 v36, v36
	v_exp_f32_e32 v37, v37
	v_add_f32_e32 v247, v34, v35
	v_cvt_pk_bf16_f32 v74, v34, v35
	s_waitcnt lgkmcnt(0)
	s_barrier
	v_mfma_f32_32x32x16_bf16 v[18:33], v[86:89], v[66:69], v[18:33]
	ds_read_b128 v[162:165], v193 offset:36864
	ds_read_b128 v[178:181], v193 offset:41472
	v_exp_f32_e32 v38, v38
	v_exp_f32_e32 v39, v39
	v_add_f32_e32 v247, v36, v247
	v_add_f32_e32 v247, v37, v247
	v_cvt_pk_bf16_f32 v75, v36, v37
	v_mfma_f32_32x32x16_bf16 v[2:17], v[216:219], v[66:69], v[2:17]
	ds_read_b128 v[166:169], v193 offset:36896
	ds_read_b128 v[182:185], v193 offset:41504
	v_exp_f32_e32 v40, v40
	v_exp_f32_e32 v41, v41
	v_add_f32_e32 v247, v38, v247
	v_add_f32_e32 v247, v39, v247
	v_cvt_pk_bf16_f32 v76, v38, v39
	v_mfma_f32_32x32x16_bf16 v[18:33], v[90:93], v[70:73], v[18:33]
	ds_read_b128 v[170:173], v193 offset:36928
	ds_read_b128 v[186:189], v193 offset:41536
	v_exp_f32_e32 v42, v42
	v_exp_f32_e32 v43, v43
	v_add_f32_e32 v247, v40, v247
	v_add_f32_e32 v247, v41, v247
	v_cvt_pk_bf16_f32 v77, v40, v41
	v_mfma_f32_32x32x16_bf16 v[2:17], v[220:223], v[70:73], v[2:17]
	ds_read_b128 v[174:177], v193 offset:36960
	ds_read_b128 v[82:85], v193 offset:41568
	v_exp_f32_e32 v44, v44
	v_exp_f32_e32 v45, v45
	v_add_f32_e32 v247, v42, v247
	v_add_f32_e32 v247, v43, v247
	v_cvt_pk_bf16_f32 v78, v42, v43
	v_mfma_f32_32x32x16_bf16 v[18:33], v[94:97], v[74:77], v[18:33]
	v_exp_f32_e32 v46, v46
	v_exp_f32_e32 v47, v47
	v_add_f32_e32 v247, v44, v247
	v_add_f32_e32 v247, v45, v247
	v_cvt_pk_bf16_f32 v79, v44, v45
	v_mfma_f32_32x32x16_bf16 v[2:17], v[224:227], v[74:77], v[2:17]
	v_exp_f32_e32 v48, v48
	v_exp_f32_e32 v49, v49
	v_add_f32_e32 v247, v46, v247
	v_add_f32_e32 v247, v47, v247
	v_cvt_pk_bf16_f32 v80, v46, v47
	v_cvt_pk_bf16_f32 v81, v48, v49
	v_add_f32_e32 v247, v48, v247
	v_add_f32_e32 v247, v49, v247
	v_mfma_f32_32x32x16_bf16 v[18:33], v[212:215], v[78:81], v[18:33]
	v_mfma_f32_32x32x16_bf16 v[2:17], v[242:245], v[78:81], v[2:17]
	v_add_f32_e32 v210, v210, v246
	v_add_f32_e32 v210, v210, v247
	s_min_i32 s24, s10, s58
	s_mul_i32 s44, s24, 0xa0000
	s_add_u32 s44, s3, s44
	s_addc_u32 s45, s12, 0
	s_lshl_b32 s46, s24, 7
	s_add_u32 s46, s15, s46
	s_addc_u32 s47, s23, 0
	global_load_dwordx4 v[146:149], v252, s[44:45] offset:1024
	global_load_dwordx4 v[150:153], v253, s[46:47]
	v_exp_f32_e32 v114, v114
	v_exp_f32_e32 v115, v115
	v_exp_f32_e32 v116, v116
	v_exp_f32_e32 v117, v117
	v_add_f32_e32 v246, v114, v115
	v_cvt_pk_bf16_f32 v114, v114, v115
	s_waitcnt lgkmcnt(0)
	v_mfma_f32_32x32x16_bf16 v[66:81], v[162:165], v[130:133], v[50:65]
	ds_read_b128 v[86:89], v248 offset:55296
	ds_read_b128 v[216:219], v248 offset:59904
	v_exp_f32_e32 v118, v118
	v_exp_f32_e32 v119, v119
	v_add_f32_e32 v246, v116, v246
	v_add_f32_e32 v246, v117, v246
	v_cvt_pk_bf16_f32 v115, v116, v117
	v_mfma_f32_32x32x16_bf16 v[34:49], v[178:181], v[130:133], v[50:65]
	ds_read_b128 v[90:93], v248 offset:55328
	ds_read_b128 v[220:223], v248 offset:59936
	v_exp_f32_e32 v120, v120
	v_exp_f32_e32 v121, v121
	v_add_f32_e32 v246, v118, v246
	v_add_f32_e32 v246, v119, v246
	v_cvt_pk_bf16_f32 v116, v118, v119
	v_mfma_f32_32x32x16_bf16 v[66:81], v[166:169], v[134:137], v[66:81]
	ds_read_b128 v[94:97], v248 offset:55360
	ds_read_b128 v[224:227], v248 offset:59968
	v_exp_f32_e32 v122, v122
	v_exp_f32_e32 v123, v123
	v_add_f32_e32 v246, v120, v246
	v_add_f32_e32 v246, v121, v246
	v_cvt_pk_bf16_f32 v117, v120, v121
	v_mfma_f32_32x32x16_bf16 v[34:49], v[182:185], v[134:137], v[34:49]
	ds_read_b128 v[212:215], v248 offset:55392
	ds_read_b128 v[242:245], v248 offset:60000
	v_exp_f32_e32 v124, v124
	v_exp_f32_e32 v125, v125
	v_add_f32_e32 v246, v122, v246
	v_add_f32_e32 v246, v123, v246
	v_cvt_pk_bf16_f32 v118, v122, v123
	v_mfma_f32_32x32x16_bf16 v[66:81], v[170:173], v[138:141], v[66:81]
	s_cmp_ge_u32 s11, s16
	s_cbranch_scc1 .Lattn_fx_skipw4
	s_waitcnt vmcnt(2)
	ds_write_b128 v192, v[154:157]
	ds_write_b128 v204, v[158:161] offset:9216
.Lattn_fx_skipw4:
	v_exp_f32_e32 v126, v126
	v_exp_f32_e32 v127, v127
	v_add_f32_e32 v246, v124, v246
	v_add_f32_e32 v246, v125, v246
	v_cvt_pk_bf16_f32 v119, v124, v125
	v_mfma_f32_32x32x16_bf16 v[34:49], v[186:189], v[138:141], v[34:49]
	v_exp_f32_e32 v128, v128
	v_exp_f32_e32 v129, v129
	v_add_f32_e32 v246, v126, v246
	v_add_f32_e32 v246, v127, v246
	v_cvt_pk_bf16_f32 v120, v126, v127
	v_mfma_f32_32x32x16_bf16 v[66:81], v[174:177], v[142:145], v[66:81]
	v_exp_f32_e32 v98, v98
	v_exp_f32_e32 v99, v99
	v_add_f32_e32 v246, v128, v246
	v_add_f32_e32 v246, v129, v246
	v_cvt_pk_bf16_f32 v121, v128, v129
	v_mfma_f32_32x32x16_bf16 v[34:49], v[82:85], v[142:145], v[34:49]
	v_exp_f32_e32 v100, v100
	v_exp_f32_e32 v101, v101
	v_add_f32_e32 v247, v98, v99
	v_cvt_pk_bf16_f32 v122, v98, v99
	s_waitcnt lgkmcnt(0)
	s_barrier
	v_mfma_f32_32x32x16_bf16 v[18:33], v[86:89], v[114:117], v[18:33]
	ds_read_b128 v[162:165], v193
	ds_read_b128 v[178:181], v193 offset:4608
	v_exp_f32_e32 v102, v102
	v_exp_f32_e32 v103, v103
	v_add_f32_e32 v247, v100, v247
	v_add_f32_e32 v247, v101, v247
	v_cvt_pk_bf16_f32 v123, v100, v101
	v_mfma_f32_32x32x16_bf16 v[2:17], v[216:219], v[114:117], v[2:17]
	ds_read_b128 v[166:169], v193 offset:32
	ds_read_b128 v[182:185], v193 offset:4640
	v_exp_f32_e32 v104, v104
	v_exp_f32_e32 v105, v105
	v_add_f32_e32 v247, v102, v247
	v_add_f32_e32 v247, v103, v247
	v_cvt_pk_bf16_f32 v124, v102, v103
	v_mfma_f32_32x32x16_bf16 v[18:33], v[90:93], v[118:121], v[18:33]
	ds_read_b128 v[170:173], v193 offset:64
	ds_read_b128 v[186:189], v193 offset:4672
	v_exp_f32_e32 v106, v106
	v_exp_f32_e32 v107, v107
	v_add_f32_e32 v247, v104, v247
	v_add_f32_e32 v247, v105, v247
	v_cvt_pk_bf16_f32 v125, v104, v105
	v_mfma_f32_32x32x16_bf16 v[2:17], v[220:223], v[118:121], v[2:17]
	ds_read_b128 v[174:177], v193 offset:96
	ds_read_b128 v[82:85], v193 offset:4704
	v_exp_f32_e32 v108, v108
	v_exp_f32_e32 v109, v109
	v_add_f32_e32 v247, v106, v247
	v_add_f32_e32 v247, v107, v247
	v_cvt_pk_bf16_f32 v126, v106, v107
	v_mfma_f32_32x32x16_bf16 v[18:33], v[94:97], v[122:125], v[18:33]
	v_exp_f32_e32 v110, v110
	v_exp_f32_e32 v111, v111
	v_add_f32_e32 v247, v108, v247
	v_add_f32_e32 v247, v109, v247
	v_cvt_pk_bf16_f32 v127, v108, v109
	v_mfma_f32_32x32x16_bf16 v[2:17], v[224:227], v[122:125], v[2:17]
	v_exp_f32_e32 v112, v112
	v_exp_f32_e32 v113, v113
	v_add_f32_e32 v247, v110, v247
	v_add_f32_e32 v247, v111, v247
	v_cvt_pk_bf16_f32 v128, v110, v111
	v_cvt_pk_bf16_f32 v129, v112, v113
	v_add_f32_e32 v247, v112, v247
	v_add_f32_e32 v247, v113, v247
	v_mfma_f32_32x32x16_bf16 v[18:33], v[212:215], v[126:129], v[18:33]
	v_mfma_f32_32x32x16_bf16 v[2:17], v[242:245], v[126:129], v[2:17]
	v_add_f32_e32 v210, v210, v246
	v_add_f32_e32 v210, v210, v247
	s_add_i32 s10, s10, 2
	s_cmp_lt_u32 s11, s16
	s_cbranch_scc0 .Lattn_fx_exit1
	s_branch .Lattn_fx_top
